# v34 = v29 + waves 4-5 skip the causal unit's drain (their last KV tile is fully masked: exact zeros)
# speedup vs baseline: 1.0026x; 1.0018x over previous
.LBB0_662:
	v_readlane_b32 s101, v246, 60
	s_nop 0
	s_and_b32 s100, s101, 6
	s_cmp_eq_u32 s100, 4
	s_cbranch_scc0 .Ldr_go
	s_waitcnt lgkmcnt(0)
	v_mov_b32_e32 v64, v100
	v_mov_b32_e32 v32, v100
	s_nop 1
	v_permlane32_swap_b32_e32 v64, v32
	s_mov_b64 s[0:1], exec
	v_readlane_b32 s8, v245, 61
	v_readlane_b32 s9, v245, 62
	s_and_b64 s[8:9], s[0:1], s[8:9]
	s_mov_b64 exec, s[8:9]
	s_cbranch_execz .LBB0_546
	v_add_f32_e32 v32, v64, v32
	ds_write_b32 v172, v32 offset:128
	s_branch .LBB0_546
